# P5 and P3c memory phases at wave priority 1, MFMA blocks at priority 0 (inverted setprio) on top of v102
# speedup vs baseline: 1.0082x; 1.0082x over previous
; #define G8_STAGE(bufoff, gbase, NM) do { _Pragma("unroll") for (int _i = 0; _i < 2; ++_i) { \
;     const char* _b = (const char*)(gbase) + (_i ? p2##NM : (size_t)0); asm volatile("" : "+s"(_b));     \
;     __builtin_amdgcn_global_load_lds((const unsigned*)(_b + voff##NM), (LAS unsigned*)(lds + (bufoff) + ldsw + _i * 8192), 16, 0, 0); } } while (0)
; #define G8_WAIT_V(n) asm volatile("s_waitcnt vmcnt(" #n ")" ::: "memory")
; #define G8_BAR __builtin_amdgcn_s_barrier()
;     ...
;   G8_STAGE(G8_SB(0, 0), cB, B); G8_STAGE(G8_SB(0, 1), cB + hstepB, B); G8_STAGE(G8_SA(0, 0), cA, A); G8_STAGE(G8_SA(0, 1), cA + hstepA, A);
;   if (wr == 1) G8_BAR;
;   G8_WAIT_V(2); G8_BAR;
;   G8_STAGE(G8_SB(1, 0), cB + kstep, B); G8_STAGE(G8_SA(1, 0), cA + kstep, A); G8_STAGE(G8_SB(1, 1), cB + hstepB + kstep, B);
;   G8_WAIT_V(6); G8_BAR;
;   for (;;) {
.LBB0_952:
	s_lshl_b32 s13, s13, 13
	s_ashr_i32 s34, s16, 1
	s_lshl_b32 s14, s14, 13
	s_and_b32 s13, s13, 0x6000
	s_add_u32 s16, s4, 0x80
	s_addc_u32 s17, s5, 0
	s_waitcnt vmcnt(2)
	s_barrier
	s_add_i32 s47, s0, 0x18000
	s_mov_b32 m0, s47
	v_lshl_add_u64 v[2:3], s[16:17], 0, v[198:199]
	s_add_u32 s16, s4, 0x4080
	s_addc_u32 s17, s5, 0
	global_load_lds_dwordx4 v[2:3], off
	s_add_i32 s48, s0, 0x1a000
	v_lshl_add_u64 v[2:3], s[16:17], 0, v[198:199]
	s_add_u32 s16, s8, 0x80
	s_mov_b32 m0, s48
	s_addc_u32 s17, s9, 0
	global_load_lds_dwordx4 v[2:3], off
	s_add_i32 s49, s0, 0x8000
	v_lshl_add_u64 v[2:3], s[16:17], 0, v[196:197]
	s_add_u32 s16, s8, 0x40080
	s_mov_b32 m0, s49
	s_addc_u32 s17, s9, 0
	global_load_lds_dwordx4 v[2:3], off
	s_add_i32 s50, s0, 0xa000
	v_lshl_add_u64 v[2:3], s[16:17], 0, v[196:197]
	s_add_u32 s16, s4, 0x8080
	s_mov_b32 m0, s50
	s_addc_u32 s17, s5, 0
	global_load_lds_dwordx4 v[2:3], off
	s_add_i32 s51, s0, 0x1c000
	s_mov_b32 m0, s51
	v_lshl_add_u64 v[2:3], s[16:17], 0, v[198:199]
	s_add_u32 s16, s4, 0xc080
	s_addc_u32 s17, s5, 0
	s_add_i32 s52, s0, 0x1e000
	global_load_lds_dwordx4 v[2:3], off
	s_mov_b32 m0, s52
	v_lshl_add_u64 v[2:3], s[16:17], 0, v[198:199]
	global_load_lds_dwordx4 v[2:3], off
	v_and_b32_e32 v1, 15, v0
	v_and_b32_e32 v2, 48, v0
	v_lshlrev_b32_e32 v0, 2, v0
	v_lshlrev_b32_e32 v1, 6, v1
	v_and_b32_e32 v0, 32, v0
	v_or_b32_e32 v3, v1, v2
	v_bitop3_b32 v1, v1, v0, v2 bitop3:0x36
	v_or_b32_e32 v1, s13, v1
	s_waitcnt vmcnt(6)
	v_bitop3_b32 v0, v3, s14, v0 bitop3:0xde
	s_cmpk_lt_u32 s12, 0x100
	v_add_u32_e32 v201, 0, v1
	s_cselect_b64 s[12:13], -1, 0
	s_add_i32 s53, s88, s89
	v_add_u32_e32 v202, 0x10000, v201
	v_add_u32_e32 v203, 0x1000, v202
	v_add_u32_e32 v204, 0, v0
	s_mov_b32 s14, 0x41800000
	s_mov_b64 s[16:17], 0x100000
	s_mov_b32 s54, 0x100000
	s_mov_b64 s[18:19], 0x120000
	s_mov_b32 s55, 0x120000
	s_mov_b64 s[20:21], 0x140000
	s_mov_b32 s56, 0x140000
	s_mov_b64 s[22:23], 0x160000
	s_mov_b32 s57, 0x160000
	s_mov_b64 s[28:29], s[8:9]
	s_setprio 1
	s_barrier
	s_branch .LBB0_955

; #define G8_STAGE(bufoff, gbase, NM) do { _Pragma("unroll") for (int _i = 0; _i < 2; ++_i) { \
;     const char* _b = (const char*)(gbase) + (_i ? p2##NM : (size_t)0); asm volatile("" : "+s"(_b));     \
;     __builtin_amdgcn_global_load_lds((const unsigned*)(_b + voff##NM), (LAS unsigned*)(lds + (bufoff) + ldsw + _i * 8192), 16, 0, 0); } } while (0)
; #define G8_WAIT_V(n) asm volatile("s_waitcnt vmcnt(" #n ")" ::: "memory")
; #define G8_WAIT_L(n) asm volatile("s_waitcnt lgkmcnt(" #n ")" ::: "memory")
; #define G8_BAR __builtin_amdgcn_s_barrier()
; #define G8_SCHED __builtin_amdgcn_sched_barrier(0)
;     ...
;       G8_LDB(B0, 0, 0); G8_LDB(B1, 0, 1); G8_SCHED; G8_LDA(At, 0, 0); G8_STAGE(G8_SA(1, 1), a1, A);
;       const bool d0a = (BD == 0) || (BD == 1 && t < (nt >> 1)) || (BD == 2 && !(cur.pn & 1));
;       const bool d1a = (BD == 0) || (BD == 1 && t >= (nt >> 1)) || (BD == 2 && !(cur.pn & 1));
;       const bool d0b = (BD == 0) || (BD == 1 && t < (nt >> 1)) || (BD == 2 && (cur.pn & 1));
;       const bool d1b = (BD == 0) || (BD == 1 && t >= (nt >> 1)) || (BD == 2 && (cur.pn & 1));
;       G8_WAIT_V(8); G8_WAIT_L(0); G8_BAR; if (d0a) G8_MMA(0, 0, At, B0); if (d1a) G8_MMA(0, 1, At, B1); G8_BAR; G8_SCHED;
;       G8_LDA(At, 0, 1); G8_STAGE(G8_SB(0, 0), b2, B); G8_STAGE(G8_SB(0, 1), b2 + hstepB, B); G8_STAGE(G8_SA(0, 0), a2, A);
;       G8_WAIT_V(8); G8_WAIT_L(0); G8_BAR; if (d0a) G8_MMA(1, 0, At, B0); if (d1a) G8_MMA(1, 1, At, B1); G8_BAR; G8_SCHED;
.LBB0_961:
	s_add_u32 s60, s8, 0x80080
	s_addc_u32 s61, s9, 0
	s_add_u32 s36, s28, 0x80
	s_addc_u32 s37, s29, 0
	s_add_u32 s38, s4, 0x80
	s_addc_u32 s39, s5, 0
	s_mov_b64 s[42:43], s[4:5]
	s_mov_b64 s[8:9], s[28:29]
	ds_read_b128 v[0:3], v202
	ds_read_b128 v[4:7], v202 offset:1024
	ds_read_b128 v[8:11], v202 offset:2048
	ds_read_b128 v[12:15], v202 offset:3072
	ds_read_b128 v[16:19], v203
	ds_read_b128 v[20:23], v203 offset:1024
	ds_read_b128 v[24:27], v203 offset:2048
	ds_read_b128 v[28:31], v203 offset:3072
	s_and_b32 s27, s34, 1
	s_cmp_eq_u32 s27, 0
	s_cselect_b64 s[44:45], -1, 0
	s_cmp_eq_u32 s27, 1
	s_cselect_b64 s[40:41], -1, 0
	s_add_i32 m0, s0, 0xc000
	s_mov_b64 s[62:63], s[60:61]
	s_add_u32 s60, s60, 0x40000
	s_waitcnt lgkmcnt(0)
	ds_read_b128 v[32:35], v204
	ds_read_b128 v[36:39], v204 offset:1024
	ds_read_b128 v[40:43], v204 offset:2048
	ds_read_b128 v[44:47], v204 offset:3072
	ds_read_b128 v[48:51], v204 offset:4096
	ds_read_b128 v[52:55], v204 offset:5120
	ds_read_b128 v[56:59], v204 offset:6144
	ds_read_b128 v[60:63], v204 offset:7168
	s_addc_u32 s61, s61, 0
	v_lshl_add_u64 v[66:67], s[62:63], 0, v[196:197]
	global_load_lds_dwordx4 v[66:67], off
	s_add_i32 m0, s0, 0xe000
	v_lshl_add_u64 v[66:67], s[60:61], 0, v[196:197]
	global_load_lds_dwordx4 v[66:67], off
	s_waitcnt vmcnt(8)
	s_waitcnt lgkmcnt(0)
	v_mov_b32_e32 v66, v65
	v_mov_b32_e32 v67, v65
	v_mov_b32_e32 v64, v65
	v_mov_b64_e32 v[86:87], v[66:67]
	v_mov_b64_e32 v[90:91], v[66:67]
	v_mov_b64_e32 v[118:119], v[66:67]
	v_mov_b64_e32 v[122:123], v[66:67]
	v_mov_b64_e32 v[150:151], v[66:67]
	v_mov_b64_e32 v[154:155], v[66:67]
	v_mov_b64_e32 v[182:183], v[66:67]
	v_mov_b64_e32 v[186:187], v[66:67]
	v_mov_b64_e32 v[94:95], v[66:67]
	v_mov_b64_e32 v[98:99], v[66:67]
	v_mov_b64_e32 v[126:127], v[66:67]
	v_mov_b64_e32 v[130:131], v[66:67]
	v_mov_b64_e32 v[158:159], v[66:67]
	v_mov_b64_e32 v[162:163], v[66:67]
	v_mov_b64_e32 v[190:191], v[66:67]
	v_mov_b64_e32 v[194:195], v[66:67]
	s_and_b64 vcc, exec, s[40:41]
	v_mov_b64_e32 v[84:85], v[64:65]
	v_mov_b64_e32 v[88:89], v[64:65]
	v_mov_b64_e32 v[116:117], v[64:65]
	v_mov_b64_e32 v[120:121], v[64:65]
	v_mov_b64_e32 v[148:149], v[64:65]
	v_mov_b64_e32 v[152:153], v[64:65]
	v_mov_b64_e32 v[180:181], v[64:65]
	v_mov_b64_e32 v[184:185], v[64:65]
	v_mov_b64_e32 v[92:93], v[64:65]
	v_mov_b64_e32 v[96:97], v[64:65]
	v_mov_b64_e32 v[124:125], v[64:65]
	v_mov_b64_e32 v[128:129], v[64:65]
	v_mov_b64_e32 v[156:157], v[64:65]
	v_mov_b64_e32 v[160:161], v[64:65]
	v_mov_b64_e32 v[188:189], v[64:65]
	v_mov_b64_e32 v[192:193], v[64:65]
	s_barrier
	s_cbranch_vccnz .LBB0_963
	s_setprio 0
	s_waitcnt lgkmcnt(0)
	v_mfma_f32_16x16x128_f8f6f4 v[192:195], v[0:7], v[32:39], 0
	v_mfma_f32_16x16x128_f8f6f4 v[188:191], v[8:15], v[32:39], 0
	v_mfma_f32_16x16x128_f8f6f4 v[160:163], v[0:7], v[40:47], 0
	v_mfma_f32_16x16x128_f8f6f4 v[156:159], v[8:15], v[40:47], 0
	v_mfma_f32_16x16x128_f8f6f4 v[128:131], v[0:7], v[48:55], 0
	v_mfma_f32_16x16x128_f8f6f4 v[124:127], v[8:15], v[48:55], 0
	v_mfma_f32_16x16x128_f8f6f4 v[96:99], v[0:7], v[56:63], 0
	v_mfma_f32_16x16x128_f8f6f4 v[92:95], v[8:15], v[56:63], 0
	v_mfma_f32_16x16x128_f8f6f4 v[184:187], v[16:23], v[32:39], 0
	v_mfma_f32_16x16x128_f8f6f4 v[180:183], v[24:31], v[32:39], 0
	v_mfma_f32_16x16x128_f8f6f4 v[152:155], v[16:23], v[40:47], 0
	v_mfma_f32_16x16x128_f8f6f4 v[148:151], v[24:31], v[40:47], 0
	v_mfma_f32_16x16x128_f8f6f4 v[120:123], v[16:23], v[48:55], 0
	v_mfma_f32_16x16x128_f8f6f4 v[116:119], v[24:31], v[48:55], 0
	v_mfma_f32_16x16x128_f8f6f4 v[88:91], v[16:23], v[56:63], 0
	v_mfma_f32_16x16x128_f8f6f4 v[84:87], v[24:31], v[56:63], 0
	s_setprio 1
.LBB0_963:
	s_barrier
	s_mov_b64 s[60:61], s[42:43]
	s_waitcnt lgkmcnt(0)
	ds_read_b128 v[32:35], v204 offset:16384
	ds_read_b128 v[36:39], v204 offset:17408
	ds_read_b128 v[40:43], v204 offset:18432
	ds_read_b128 v[44:47], v204 offset:19456
	ds_read_b128 v[48:51], v204 offset:20480
	ds_read_b128 v[52:55], v204 offset:21504
	ds_read_b128 v[56:59], v204 offset:22528
	ds_read_b128 v[60:63], v204 offset:23552
	s_mov_b32 m0, s1
	v_lshl_add_u64 v[66:67], s[60:61], 0, v[198:199]
	s_add_u32 s60, s42, 0x4000
	s_addc_u32 s61, s43, 0
	global_load_lds_dwordx4 v[66:67], off
	s_mov_b32 m0, s2
	v_lshl_add_u64 v[66:67], s[60:61], 0, v[198:199]
	s_add_u32 s60, s42, 0x8000
	s_addc_u32 s61, s43, 0
	s_add_u32 s42, s42, 0xc000
	global_load_lds_dwordx4 v[66:67], off
	s_mov_b32 m0, s3
	v_lshl_add_u64 v[66:67], s[60:61], 0, v[198:199]
	s_addc_u32 s43, s43, 0
	global_load_lds_dwordx4 v[66:67], off
	s_mov_b32 m0, s15
	v_lshl_add_u64 v[66:67], s[42:43], 0, v[198:199]
	s_mov_b64 s[42:43], s[8:9]
	global_load_lds_dwordx4 v[66:67], off
	s_mov_b32 m0, s0
	v_lshl_add_u64 v[66:67], s[42:43], 0, v[196:197]
	s_add_u32 s42, s8, 0x40000
	s_addc_u32 s43, s9, 0
	global_load_lds_dwordx4 v[66:67], off
	s_mov_b32 m0, s31
	v_lshl_add_u64 v[66:67], s[42:43], 0, v[196:197]
	global_load_lds_dwordx4 v[66:67], off
	s_waitcnt vmcnt(8)
	s_waitcnt lgkmcnt(0)
	s_andn2_b64 vcc, exec, s[44:45]
	s_barrier
	s_cbranch_vccnz .LBB0_965
	s_setprio 0
	s_waitcnt lgkmcnt(0)
	v_mfma_f32_16x16x128_f8f6f4 v[176:179], v[0:7], v[32:39], 0
	v_mfma_f32_16x16x128_f8f6f4 v[172:175], v[8:15], v[32:39], 0
	v_mfma_f32_16x16x128_f8f6f4 v[144:147], v[0:7], v[40:47], 0
	v_mfma_f32_16x16x128_f8f6f4 v[140:143], v[8:15], v[40:47], 0
	v_mfma_f32_16x16x128_f8f6f4 v[112:115], v[0:7], v[48:55], 0
	v_mfma_f32_16x16x128_f8f6f4 v[108:111], v[8:15], v[48:55], 0
	v_mfma_f32_16x16x128_f8f6f4 v[80:83], v[0:7], v[56:63], 0
	v_mfma_f32_16x16x128_f8f6f4 v[76:79], v[8:15], v[56:63], 0
	v_mfma_f32_16x16x128_f8f6f4 v[168:171], v[16:23], v[32:39], 0
	v_mfma_f32_16x16x128_f8f6f4 v[164:167], v[24:31], v[32:39], 0
	v_mfma_f32_16x16x128_f8f6f4 v[136:139], v[16:23], v[40:47], 0
	v_mfma_f32_16x16x128_f8f6f4 v[132:135], v[24:31], v[40:47], 0
	v_mfma_f32_16x16x128_f8f6f4 v[104:107], v[16:23], v[48:55], 0
	v_mfma_f32_16x16x128_f8f6f4 v[100:103], v[24:31], v[48:55], 0
	v_mfma_f32_16x16x128_f8f6f4 v[72:75], v[16:23], v[56:63], 0
	v_mfma_f32_16x16x128_f8f6f4 v[68:71], v[24:31], v[56:63], 0
	s_setprio 1
	s_branch .LBB0_966

; #define G8_STAGE(bufoff, gbase, NM) do { _Pragma("unroll") for (int _i = 0; _i < 2; ++_i) { \
;     const char* _b = (const char*)(gbase) + (_i ? p2##NM : (size_t)0); asm volatile("" : "+s"(_b));     \
;     __builtin_amdgcn_global_load_lds((const unsigned*)(_b + voff##NM), (LAS unsigned*)(lds + (bufoff) + ldsw + _i * 8192), 16, 0, 0); } } while (0)
; #define G8_WAIT_V(n) asm volatile("s_waitcnt vmcnt(" #n ")" ::: "memory")
; #define G8_WAIT_L(n) asm volatile("s_waitcnt lgkmcnt(" #n ")" ::: "memory")
; #define G8_BAR __builtin_amdgcn_s_barrier()
; #define G8_SCHED __builtin_amdgcn_sched_barrier(0)
;     ...
;       G8_LDB(B0, 1, 0); G8_LDB(B1, 1, 1); G8_SCHED; G8_LDA(At, 1, 0); G8_STAGE(G8_SA(0, 1), a2 + hstepA, A);
;       G8_WAIT_V(8); G8_WAIT_L(0); G8_BAR; if (d0b) G8_MMA(0, 0, At, B0); if (d1b) G8_MMA(0, 1, At, B1); G8_BAR; G8_SCHED;
;       G8_LDA(At, 1, 1); G8_STAGE(G8_SB(1, 0), b3, B); G8_STAGE(G8_SB(1, 1), b3 + hstepB, B); G8_STAGE(G8_SA(1, 0), a3, A);
;       G8_WAIT_V(8); G8_WAIT_L(0); G8_BAR; if (d0b) G8_MMA(1, 0, At, B0); if (d1b) G8_MMA(1, 1, At, B1); G8_BAR; G8_SCHED;
.LBB0_966:
	s_barrier
	v_add_u32_e32 v12, 0x18000, v201
	v_add_u32_e32 v28, 0x1000, v12
	ds_read_b128 v[0:3], v12
	ds_read_b128 v[4:7], v12 offset:1024
	ds_read_b128 v[8:11], v12 offset:2048
	ds_read_b128 v[12:15], v12 offset:3072
	ds_read_b128 v[16:19], v28
	ds_read_b128 v[20:23], v28 offset:1024
	ds_read_b128 v[24:27], v28 offset:2048
	ds_read_b128 v[28:31], v28 offset:3072
	s_add_u32 s42, s8, 0x80000
	s_addc_u32 s43, s9, 0
	s_add_u32 s8, s8, 0xc0000
	s_mov_b32 m0, s33
	s_waitcnt lgkmcnt(0)
	ds_read_b128 v[32:35], v204 offset:32768
	ds_read_b128 v[36:39], v204 offset:33792
	ds_read_b128 v[40:43], v204 offset:34816
	ds_read_b128 v[44:47], v204 offset:35840
	ds_read_b128 v[48:51], v204 offset:36864
	ds_read_b128 v[52:55], v204 offset:37888
	ds_read_b128 v[56:59], v204 offset:38912
	ds_read_b128 v[60:63], v204 offset:39936
	s_addc_u32 s9, s9, 0
	v_lshl_add_u64 v[66:67], s[42:43], 0, v[196:197]
	global_load_lds_dwordx4 v[66:67], off
	s_mov_b32 m0, s46
	v_lshl_add_u64 v[66:67], s[8:9], 0, v[196:197]
	global_load_lds_dwordx4 v[66:67], off
	s_waitcnt vmcnt(8)
	s_waitcnt lgkmcnt(0)
	v_cndmask_b32_e64 v64, 0, 1, s[40:41]
	v_cmp_ne_u32_e64 s[8:9], 1, v64
	s_andn2_b64 vcc, exec, s[40:41]
	s_barrier
	s_cbranch_vccnz .LBB0_968
	s_setprio 0
	s_waitcnt lgkmcnt(0)
	v_mfma_f32_16x16x128_f8f6f4 v[192:195], v[0:7], v[32:39], v[192:195]
	v_mfma_f32_16x16x128_f8f6f4 v[188:191], v[8:15], v[32:39], v[188:191]
	v_mfma_f32_16x16x128_f8f6f4 v[160:163], v[0:7], v[40:47], v[160:163]
	v_mfma_f32_16x16x128_f8f6f4 v[156:159], v[8:15], v[40:47], v[156:159]
	v_mfma_f32_16x16x128_f8f6f4 v[128:131], v[0:7], v[48:55], v[128:131]
	v_mfma_f32_16x16x128_f8f6f4 v[124:127], v[8:15], v[48:55], v[124:127]
	v_mfma_f32_16x16x128_f8f6f4 v[96:99], v[0:7], v[56:63], v[96:99]
	v_mfma_f32_16x16x128_f8f6f4 v[92:95], v[8:15], v[56:63], v[92:95]
	v_mfma_f32_16x16x128_f8f6f4 v[184:187], v[16:23], v[32:39], v[184:187]
	v_mfma_f32_16x16x128_f8f6f4 v[180:183], v[24:31], v[32:39], v[180:183]
	v_mfma_f32_16x16x128_f8f6f4 v[152:155], v[16:23], v[40:47], v[152:155]
	v_mfma_f32_16x16x128_f8f6f4 v[148:151], v[24:31], v[40:47], v[148:151]
	v_mfma_f32_16x16x128_f8f6f4 v[120:123], v[16:23], v[48:55], v[120:123]
	v_mfma_f32_16x16x128_f8f6f4 v[116:119], v[24:31], v[48:55], v[116:119]
	v_mfma_f32_16x16x128_f8f6f4 v[88:91], v[16:23], v[56:63], v[88:91]
	v_mfma_f32_16x16x128_f8f6f4 v[84:87], v[24:31], v[56:63], v[84:87]
	s_setprio 1
.LBB0_968:
	s_barrier
	s_mov_b64 s[40:41], s[38:39]
	s_waitcnt lgkmcnt(0)
	ds_read_b128 v[32:35], v204 offset:49152
	ds_read_b128 v[36:39], v204 offset:50176
	ds_read_b128 v[40:43], v204 offset:51200
	ds_read_b128 v[44:47], v204 offset:52224
	ds_read_b128 v[48:51], v204 offset:53248
	ds_read_b128 v[52:55], v204 offset:54272
	ds_read_b128 v[56:59], v204 offset:55296
	ds_read_b128 v[60:63], v204 offset:56320
	s_mov_b32 m0, s47
	v_lshl_add_u64 v[66:67], s[40:41], 0, v[198:199]
	s_add_u32 s40, s38, 0x4000
	s_addc_u32 s41, s39, 0
	global_load_lds_dwordx4 v[66:67], off
	s_mov_b32 m0, s48
	v_lshl_add_u64 v[66:67], s[40:41], 0, v[198:199]
	s_add_u32 s40, s38, 0x8000
	s_addc_u32 s41, s39, 0
	s_add_u32 s38, s38, 0xc000
	global_load_lds_dwordx4 v[66:67], off
	s_mov_b32 m0, s51
	v_lshl_add_u64 v[66:67], s[40:41], 0, v[198:199]
	s_addc_u32 s39, s39, 0
	global_load_lds_dwordx4 v[66:67], off
	s_mov_b32 m0, s52
	v_lshl_add_u64 v[66:67], s[38:39], 0, v[198:199]
	s_mov_b64 s[38:39], s[36:37]
	s_add_u32 s36, s36, 0x40000
	global_load_lds_dwordx4 v[66:67], off
	s_mov_b32 m0, s49
	v_lshl_add_u64 v[66:67], s[38:39], 0, v[196:197]
	s_addc_u32 s37, s37, 0
	global_load_lds_dwordx4 v[66:67], off
	s_mov_b32 m0, s50
	v_lshl_add_u64 v[66:67], s[36:37], 0, v[196:197]
	global_load_lds_dwordx4 v[66:67], off
	s_waitcnt vmcnt(8)
	s_waitcnt lgkmcnt(0)
	s_and_b64 vcc, exec, s[8:9]
	s_barrier
	s_cbranch_vccnz .LBB0_970
	s_setprio 0
	s_waitcnt lgkmcnt(0)
	v_mfma_f32_16x16x128_f8f6f4 v[176:179], v[0:7], v[32:39], v[176:179]
	v_mfma_f32_16x16x128_f8f6f4 v[172:175], v[8:15], v[32:39], v[172:175]
	v_mfma_f32_16x16x128_f8f6f4 v[144:147], v[0:7], v[40:47], v[144:147]
	v_mfma_f32_16x16x128_f8f6f4 v[140:143], v[8:15], v[40:47], v[140:143]
	v_mfma_f32_16x16x128_f8f6f4 v[112:115], v[0:7], v[48:55], v[112:115]
	v_mfma_f32_16x16x128_f8f6f4 v[108:111], v[8:15], v[48:55], v[108:111]
	v_mfma_f32_16x16x128_f8f6f4 v[80:83], v[0:7], v[56:63], v[80:83]
	v_mfma_f32_16x16x128_f8f6f4 v[76:79], v[8:15], v[56:63], v[76:79]
	v_mfma_f32_16x16x128_f8f6f4 v[168:171], v[16:23], v[32:39], v[168:171]
	v_mfma_f32_16x16x128_f8f6f4 v[164:167], v[24:31], v[32:39], v[164:167]
	v_mfma_f32_16x16x128_f8f6f4 v[136:139], v[16:23], v[40:47], v[136:139]
	v_mfma_f32_16x16x128_f8f6f4 v[132:135], v[24:31], v[40:47], v[132:135]
	v_mfma_f32_16x16x128_f8f6f4 v[104:107], v[16:23], v[48:55], v[104:107]
	v_mfma_f32_16x16x128_f8f6f4 v[100:103], v[24:31], v[48:55], v[100:103]
	v_mfma_f32_16x16x128_f8f6f4 v[72:75], v[16:23], v[56:63], v[72:75]
	v_mfma_f32_16x16x128_f8f6f4 v[68:71], v[24:31], v[56:63], v[68:71]
	s_setprio 1

; #define G8_WAIT_V(n) asm volatile("s_waitcnt vmcnt(" #n ")" ::: "memory")
; #define G8_BAR __builtin_amdgcn_s_barrier()
;     ...
;   G8_WAIT_V(0);
;   G8_BAR;
.LBB0_975:
	s_setprio 0
	s_waitcnt vmcnt(0)
	s_barrier

; #define G8_STAGE(bufoff, gbase, NM) do { _Pragma("unroll") for (int _i = 0; _i < 2; ++_i) { \
;     const char* _b = (const char*)(gbase) + (_i ? p2##NM : (size_t)0); asm volatile("" : "+s"(_b));     \
;     __builtin_amdgcn_global_load_lds((const unsigned*)(_b + voff##NM), (LAS unsigned*)(lds + (bufoff) + ldsw + _i * 8192), 16, 0, 0); } } while (0)
; #define G8_WAIT_V(n) asm volatile("s_waitcnt vmcnt(" #n ")" ::: "memory")
; #define G8_BAR __builtin_amdgcn_s_barrier()
;     ...
;   G8_STAGE(G8_SB(0, 0), cB, B); G8_STAGE(G8_SB(0, 1), cB + hstepB, B); G8_STAGE(G8_SA(0, 0), cA, A); G8_STAGE(G8_SA(0, 1), cA + hstepA, A);
;   if (wr == 1) G8_BAR;
;   G8_WAIT_V(2); G8_BAR;
;   G8_STAGE(G8_SB(1, 0), cB + kstep, B); G8_STAGE(G8_SA(1, 0), cA + kstep, A); G8_STAGE(G8_SB(1, 1), cB + hstepB + kstep, B);
;   G8_WAIT_V(6); G8_BAR;
;   for (;;) {
.LBB0_1035:
	s_lshl_b32 s12, s12, 12
	s_lshl_b32 s16, s14, 13
	s_and_b32 s12, s12, 0x3000
	s_add_u32 s14, s36, 0x80
	s_addc_u32 s15, s37, 0
	s_waitcnt vmcnt(2)
	s_barrier
	s_add_i32 m0, s1, 0x18000
	v_and_b32_e32 v1, 15, v0
	v_lshl_add_u64 v[2:3], s[14:15], 0, v[130:131]
	s_add_u32 s14, s36, 0x8080
	s_addc_u32 s15, s37, 0
	global_load_lds_dwordx4 v[2:3], off
	s_add_i32 m0, s1, 0x1a000
	v_lshl_add_u64 v[2:3], s[14:15], 0, v[130:131]
	s_add_u32 s14, s30, 0x80
	s_addc_u32 s15, s31, 0
	global_load_lds_dwordx4 v[2:3], off
	s_add_i32 s29, s1, 0x8000
	v_lshl_add_u64 v[2:3], s[14:15], 0, v[128:129]
	s_add_u32 s14, s30, 0x80080
	s_mov_b32 m0, s29
	s_addc_u32 s15, s31, 0
	global_load_lds_dwordx4 v[2:3], off
	s_add_i32 s33, s1, 0xa000
	v_lshl_add_u64 v[2:3], s[14:15], 0, v[128:129]
	s_add_u32 s14, s36, 0x10080
	s_mov_b32 m0, s33
	s_addc_u32 s15, s37, 0
	global_load_lds_dwordx4 v[2:3], off
	s_add_i32 m0, s1, 0x1c000
	v_lshlrev_b32_e32 v1, 6, v1
	v_lshl_add_u64 v[2:3], s[14:15], 0, v[130:131]
	s_add_u32 s14, s36, 0x18080
	s_addc_u32 s15, s37, 0
	global_load_lds_dwordx4 v[2:3], off
	s_add_i32 m0, s1, 0x1e000
	v_lshl_add_u64 v[2:3], s[14:15], 0, v[130:131]
	global_load_lds_dwordx4 v[2:3], off
	v_and_b32_e32 v2, 48, v0
	v_lshlrev_b32_e32 v0, 2, v0
	v_and_b32_e32 v0, 32, v0
	v_or_b32_e32 v3, v1, v2
	v_bitop3_b32 v1, v1, v0, v2 bitop3:0x36
	s_waitcnt vmcnt(6)
	s_cmpk_lt_u32 s11, 0x100
	s_sext_i32_i8 s46, s10
	v_bitop3_b32 v0, v3, s16, v0 bitop3:0xde
	v_or_b32_e32 v138, s12, v1
	s_cselect_b64 s[10:11], -1, 0
	s_add_i32 s43, 0, 0x10000
	s_add_i32 s44, 0, 0x14000
	s_add_i32 s42, s88, s89
	v_add_u32_e32 v139, s43, v138
	v_add_u32_e32 v140, 0, v0
	v_add_u32_e32 v141, s44, v138
	s_mov_b32 s12, 0x41800000
	s_mov_b64 s[14:15], 0x90000
	s_mov_b64 s[16:17], 0xa0000
	s_mov_b64 s[18:19], 0xb0000
	s_setprio 1
	s_barrier
	s_branch .LBB0_1038

; #define G8_STAGE(bufoff, gbase, NM) do { _Pragma("unroll") for (int _i = 0; _i < 2; ++_i) { \
;     const char* _b = (const char*)(gbase) + (_i ? p2##NM : (size_t)0); asm volatile("" : "+s"(_b));     \
;     __builtin_amdgcn_global_load_lds((const unsigned*)(_b + voff##NM), (LAS unsigned*)(lds + (bufoff) + ldsw + _i * 8192), 16, 0, 0); } } while (0)
; #define G8_WAIT_V(n) asm volatile("s_waitcnt vmcnt(" #n ")" ::: "memory")
; #define G8_WAIT_L(n) asm volatile("s_waitcnt lgkmcnt(" #n ")" ::: "memory")
; #define G8_BAR __builtin_amdgcn_s_barrier()
; #define G8_SCHED __builtin_amdgcn_sched_barrier(0)
;     ...
;       G8_LDB(B0, 0, 0); G8_LDB(B1, 0, 1); G8_SCHED; G8_LDA(At, 0, 0); G8_STAGE(G8_SA(1, 1), a1, A);
;       const bool d0a = (BD == 0) || (BD == 1 && t < (nt >> 1)) || (BD == 2 && !(cur.pn & 1));
;       const bool d1a = (BD == 0) || (BD == 1 && t >= (nt >> 1)) || (BD == 2 && !(cur.pn & 1));
;       const bool d0b = (BD == 0) || (BD == 1 && t < (nt >> 1)) || (BD == 2 && (cur.pn & 1));
;       const bool d1b = (BD == 0) || (BD == 1 && t >= (nt >> 1)) || (BD == 2 && (cur.pn & 1));
;       G8_WAIT_V(8); G8_WAIT_L(0); G8_BAR; if (d0a) G8_MMA(0, 0, At, B0); if (d1a) G8_MMA(0, 1, At, B1); G8_BAR; G8_SCHED;
;       G8_LDA(At, 0, 1); G8_STAGE(G8_SB(0, 0), b2, B); G8_STAGE(G8_SB(0, 1), b2 + hstepB, B); G8_STAGE(G8_SA(0, 0), a2, A);
;       G8_WAIT_V(8); G8_WAIT_L(0); G8_BAR; if (d0a) G8_MMA(1, 0, At, B0); if (d1a) G8_MMA(1, 1, At, B1); G8_BAR; G8_SCHED;
;       G8_LDB(B0, 1, 0); G8_LDB(B1, 1, 1); G8_SCHED; G8_LDA(At, 1, 0); G8_STAGE(G8_SA(0, 1), a2 + hstepA, A);
;       G8_WAIT_V(8); G8_WAIT_L(0); G8_BAR; if (d0b) G8_MMA(0, 0, At, B0); if (d1b) G8_MMA(0, 1, At, B1); G8_BAR; G8_SCHED;
.LBB0_1045:
	s_add_u32 s48, s30, 0x100080
	s_addc_u32 s49, s31, 0
	s_add_u32 s38, s30, 0x100
	s_addc_u32 s39, s31, 0
	s_add_u32 s40, s36, 0x100
	s_addc_u32 s41, s37, 0
	s_add_u32 s34, s30, 0x180
	s_addc_u32 s35, s31, 0
	s_add_u32 s36, s36, 0x180
	s_addc_u32 s37, s37, 0
	ds_read_b128 v[0:3], v139
	ds_read_b128 v[4:7], v139 offset:1024
	ds_read_b128 v[8:11], v139 offset:2048
	ds_read_b128 v[12:15], v139 offset:3072
	s_mov_b64 s[50:51], s[48:49]
	ds_read_b128 v[16:19], v140
	ds_read_b128 v[20:23], v140 offset:1024
	ds_read_b128 v[24:27], v140 offset:2048
	ds_read_b128 v[28:31], v140 offset:3072
	ds_read_b128 v[32:35], v140 offset:4096
	ds_read_b128 v[36:39], v140 offset:5120
	ds_read_b128 v[40:43], v140 offset:6144
	ds_read_b128 v[44:47], v140 offset:7168
	s_nop 0
	v_lshl_add_u64 v[48:49], s[50:51], 0, v[128:129]
	s_add_i32 s51, s1, 0xc000
	s_add_u32 s48, s48, 0x80000
	s_mov_b32 m0, s51
	s_addc_u32 s49, s49, 0
	s_add_i32 s23, s1, 0xe000
	global_load_lds_dwordx4 v[48:49], off
	s_mov_b32 m0, s23
	v_lshl_add_u64 v[48:49], s[48:49], 0, v[128:129]
	global_load_lds_dwordx4 v[48:49], off
	s_waitcnt vmcnt(8)
	s_waitcnt lgkmcnt(0)
	s_barrier
	s_setprio 0
	s_waitcnt lgkmcnt(0)
	v_mfma_f32_16x16x128_f8f6f4 v[48:51], v[0:7], v[16:23], 0
	v_mfma_f32_16x16x128_f8f6f4 v[52:55], v[8:15], v[16:23], 0
	v_mfma_f32_16x16x128_f8f6f4 v[56:59], v[0:7], v[24:31], 0
	v_mfma_f32_16x16x128_f8f6f4 v[60:63], v[8:15], v[24:31], 0
	v_mfma_f32_16x16x128_f8f6f4 v[64:67], v[0:7], v[32:39], 0
	v_mfma_f32_16x16x128_f8f6f4 v[68:71], v[8:15], v[32:39], 0
	v_mfma_f32_16x16x128_f8f6f4 v[80:83], v[0:7], v[40:47], 0
	v_mfma_f32_16x16x128_f8f6f4 v[84:87], v[8:15], v[40:47], 0
	s_setprio 1
	s_barrier
	s_mov_b64 s[48:49], s[40:41]
	ds_read_b128 v[16:19], v140 offset:16384
	ds_read_b128 v[20:23], v140 offset:17408
	ds_read_b128 v[24:27], v140 offset:18432
	ds_read_b128 v[28:31], v140 offset:19456
	ds_read_b128 v[32:35], v140 offset:20480
	ds_read_b128 v[36:39], v140 offset:21504
	ds_read_b128 v[40:43], v140 offset:22528
	ds_read_b128 v[44:47], v140 offset:23552
	s_add_i32 s52, s43, s0
	v_lshl_add_u64 v[72:73], s[48:49], 0, v[130:131]
	s_add_u32 s48, s40, 0x8000
	s_mov_b32 m0, s52
	s_addc_u32 s49, s41, 0
	global_load_lds_dwordx4 v[72:73], off
	s_add_i32 s47, s52, 0x2000
	v_lshl_add_u64 v[72:73], s[48:49], 0, v[130:131]
	s_add_u32 s48, s40, 0x10000
	s_mov_b32 m0, s47
	s_addc_u32 s49, s41, 0
	global_load_lds_dwordx4 v[72:73], off
	s_mov_b64 s[54:55], s[38:39]
	v_lshl_add_u64 v[72:73], s[48:49], 0, v[130:131]
	s_add_i32 s48, s44, s0
	s_add_u32 s40, s40, 0x18000
	s_mov_b32 m0, s48
	s_addc_u32 s41, s41, 0
	global_load_lds_dwordx4 v[72:73], off
	s_nop 0
	v_lshl_add_u64 v[72:73], s[40:41], 0, v[130:131]
	s_add_i32 s40, s48, 0x2000
	s_mov_b32 m0, s40
	s_nop 0
	global_load_lds_dwordx4 v[72:73], off
	s_mov_b32 m0, s1
	v_lshl_add_u64 v[72:73], s[54:55], 0, v[128:129]
	s_add_u32 s54, s38, 0x80000
	s_addc_u32 s55, s39, 0
	global_load_lds_dwordx4 v[72:73], off
	s_mov_b32 m0, s2
	v_lshl_add_u64 v[72:73], s[54:55], 0, v[128:129]
	global_load_lds_dwordx4 v[72:73], off
	s_waitcnt vmcnt(8)
	s_waitcnt lgkmcnt(0)
	s_barrier
	s_setprio 0
	s_waitcnt lgkmcnt(0)
	v_mfma_f32_16x16x128_f8f6f4 v[96:99], v[0:7], v[16:23], 0
	v_mfma_f32_16x16x128_f8f6f4 v[100:103], v[8:15], v[16:23], 0
	v_mfma_f32_16x16x128_f8f6f4 v[112:115], v[0:7], v[24:31], 0
	v_mfma_f32_16x16x128_f8f6f4 v[116:119], v[8:15], v[24:31], 0
	v_mfma_f32_16x16x128_f8f6f4 v[120:123], v[0:7], v[32:39], 0
	v_mfma_f32_16x16x128_f8f6f4 v[124:127], v[8:15], v[32:39], 0
	v_mfma_f32_16x16x128_f8f6f4 v[132:135], v[0:7], v[40:47], 0
	v_mfma_f32_16x16x128_f8f6f4 v[142:145], v[8:15], v[40:47], 0
	s_setprio 1
	s_barrier
	s_add_i32 s53, 0, 0x18000
	v_add_u32_e32 v8, s53, v138
	ds_read_b128 v[0:3], v8
	ds_read_b128 v[4:7], v8 offset:1024
	ds_read_b128 v[16:19], v8 offset:2048
	ds_read_b128 v[20:23], v8 offset:3072
	s_add_u32 s54, s38, 0x100000
	s_addc_u32 s55, s39, 0
	s_add_u32 s38, s38, 0x180000
	s_mov_b32 m0, s3
	ds_read_b128 v[8:11], v140 offset:32768
	ds_read_b128 v[12:15], v140 offset:33792
	ds_read_b128 v[24:27], v140 offset:34816
	ds_read_b128 v[28:31], v140 offset:35840
	ds_read_b128 v[32:35], v140 offset:36864
	ds_read_b128 v[36:39], v140 offset:37888
	ds_read_b128 v[40:43], v140 offset:38912
	ds_read_b128 v[44:47], v140 offset:39936
	s_addc_u32 s39, s39, 0
	v_lshl_add_u64 v[72:73], s[54:55], 0, v[128:129]
	global_load_lds_dwordx4 v[72:73], off
	s_mov_b32 m0, s13
	v_lshl_add_u64 v[72:73], s[38:39], 0, v[128:129]
	global_load_lds_dwordx4 v[72:73], off
	s_waitcnt vmcnt(8)
	s_waitcnt lgkmcnt(0)
	s_barrier
	s_setprio 0
	s_waitcnt lgkmcnt(0)
	v_mfma_f32_16x16x128_f8f6f4 v[108:111], v[0:7], v[8:15], v[48:51]
	v_mfma_f32_16x16x128_f8f6f4 v[104:107], v[16:23], v[8:15], v[52:55]
	v_mfma_f32_16x16x128_f8f6f4 v[92:95], v[0:7], v[24:31], v[56:59]
	v_mfma_f32_16x16x128_f8f6f4 v[88:91], v[16:23], v[24:31], v[60:63]
	v_mfma_f32_16x16x128_f8f6f4 v[76:79], v[0:7], v[32:39], v[64:67]
	v_mfma_f32_16x16x128_f8f6f4 v[72:75], v[16:23], v[32:39], v[68:71]
	v_mfma_f32_16x16x128_f8f6f4 v[60:63], v[0:7], v[40:47], v[80:83]
	v_mfma_f32_16x16x128_f8f6f4 v[56:59], v[16:23], v[40:47], v[84:87]
	s_setprio 1
	s_barrier
; #define G8_STAGE(bufoff, gbase, NM) do { _Pragma("unroll") for (int _i = 0; _i < 2; ++_i) { \
;     const char* _b = (const char*)(gbase) + (_i ? p2##NM : (size_t)0); asm volatile("" : "+s"(_b));     \
;     __builtin_amdgcn_global_load_lds((const unsigned*)(_b + voff##NM), (LAS unsigned*)(lds + (bufoff) + ldsw + _i * 8192), 16, 0, 0); } } while (0)
; #define G8_WAIT_V(n) asm volatile("s_waitcnt vmcnt(" #n ")" ::: "memory")
; #define G8_WAIT_L(n) asm volatile("s_waitcnt lgkmcnt(" #n ")" ::: "memory")
; #define G8_BAR __builtin_amdgcn_s_barrier()
; #define G8_SCHED __builtin_amdgcn_sched_barrier(0)
;     ...
;       G8_LDB(B0, 0, 0); G8_LDB(B1, 0, 1); G8_SCHED; G8_LDA(At, 0, 0); G8_STAGE(G8_SA(1, 1), a1, A);
;       const bool d0a = (BD == 0) || (BD == 1 && t < (nt >> 1)) || (BD == 2 && !(cur.pn & 1));
;       const bool d1a = (BD == 0) || (BD == 1 && t >= (nt >> 1)) || (BD == 2 && !(cur.pn & 1));
;       const bool d0b = (BD == 0) || (BD == 1 && t < (nt >> 1)) || (BD == 2 && (cur.pn & 1));
;       const bool d1b = (BD == 0) || (BD == 1 && t >= (nt >> 1)) || (BD == 2 && (cur.pn & 1));
;       G8_WAIT_V(8); G8_WAIT_L(0); G8_BAR; if (d0a) G8_MMA(0, 0, At, B0); if (d1a) G8_MMA(0, 1, At, B1); G8_BAR; G8_SCHED;
;       G8_LDA(At, 0, 1); G8_STAGE(G8_SB(0, 0), b2, B); G8_STAGE(G8_SB(0, 1), b2 + hstepB, B); G8_STAGE(G8_SA(0, 0), a2, A);
;       G8_WAIT_V(8); G8_WAIT_L(0); G8_BAR; if (d0a) G8_MMA(1, 0, At, B0); if (d1a) G8_MMA(1, 1, At, B1); G8_BAR; G8_SCHED;
;     ...
;       G8_WAIT_V(8); G8_WAIT_L(0); G8_BAR; if (d0b) G8_MMA(0, 0, At, B0); if (d1b) G8_MMA(0, 1, At, B1); G8_BAR; G8_SCHED;
;       G8_LDA(At, 1, 1); G8_STAGE(G8_SB(1, 0), b3, B); G8_STAGE(G8_SB(1, 1), b3 + hstepB, B); G8_STAGE(G8_SA(1, 0), a3, A);
;       G8_WAIT_V(8); G8_WAIT_L(0); G8_BAR; if (d0b) G8_MMA(1, 0, At, B0); if (d1b) G8_MMA(1, 1, At, B1); G8_BAR; G8_SCHED;
	s_mov_b64 s[38:39], s[36:37]
	ds_read_b128 v[8:11], v140 offset:49152
	ds_read_b128 v[12:15], v140 offset:50176
	ds_read_b128 v[32:35], v140 offset:51200
	ds_read_b128 v[36:39], v140 offset:52224
	ds_read_b128 v[48:51], v140 offset:53248
	ds_read_b128 v[52:55], v140 offset:54272
	ds_read_b128 v[64:67], v140 offset:55296
	ds_read_b128 v[68:71], v140 offset:56320
	s_add_i32 s53, s53, s0
	v_lshl_add_u64 v[24:25], s[38:39], 0, v[130:131]
	s_add_u32 s38, s36, 0x8000
	s_mov_b32 m0, s53
	s_addc_u32 s39, s37, 0
	global_load_lds_dwordx4 v[24:25], off
	s_add_i32 s41, s53, 0x2000
	v_lshl_add_u64 v[24:25], s[38:39], 0, v[130:131]
	s_add_u32 s38, s36, 0x10000
	s_addc_u32 s39, s37, 0
	s_add_i32 s54, 0, 0x1c000
	s_add_i32 s49, s54, s0
	s_mov_b32 m0, s41
	s_add_u32 s36, s36, 0x18000
	global_load_lds_dwordx4 v[24:25], off
	s_mov_b32 m0, s49
	v_lshl_add_u64 v[24:25], s[38:39], 0, v[130:131]
	s_addc_u32 s37, s37, 0
	global_load_lds_dwordx4 v[24:25], off
	s_add_i32 s50, s49, 0x2000
	v_lshl_add_u64 v[24:25], s[36:37], 0, v[130:131]
	s_mov_b32 m0, s50
	s_mov_b64 s[36:37], s[34:35]
	s_add_u32 s34, s34, 0x80000
	global_load_lds_dwordx4 v[24:25], off
	s_mov_b32 m0, s29
	v_lshl_add_u64 v[24:25], s[36:37], 0, v[128:129]
	s_addc_u32 s35, s35, 0
	global_load_lds_dwordx4 v[24:25], off
	s_mov_b32 m0, s33
	v_lshl_add_u64 v[24:25], s[34:35], 0, v[128:129]
	global_load_lds_dwordx4 v[24:25], off
	s_waitcnt vmcnt(8)
	s_waitcnt lgkmcnt(0)
	s_barrier
	s_setprio 0
	s_waitcnt lgkmcnt(0)
	v_mfma_f32_16x16x128_f8f6f4 v[44:47], v[0:7], v[8:15], v[96:99]
	v_mfma_f32_16x16x128_f8f6f4 v[40:43], v[16:23], v[8:15], v[100:103]
	v_mfma_f32_16x16x128_f8f6f4 v[28:31], v[0:7], v[32:39], v[112:115]
	v_mfma_f32_16x16x128_f8f6f4 v[24:27], v[16:23], v[32:39], v[116:119]
	v_mfma_f32_16x16x128_f8f6f4 v[12:15], v[0:7], v[48:55], v[120:123]
	v_mfma_f32_16x16x128_f8f6f4 v[8:11], v[16:23], v[48:55], v[124:127]
	v_mfma_f32_16x16x128_f8f6f4 v[4:7], v[0:7], v[64:71], v[132:135]
	v_mfma_f32_16x16x128_f8f6f4 v[0:3], v[16:23], v[64:71], v[142:145]
	s_setprio 1
	s_barrier
	s_add_u32 s56, s30, 0x100180
	s_addc_u32 s57, s31, 0
	s_add_u32 s30, s24, 0x80
	s_addc_u32 s31, s25, 0
	s_add_u32 s34, s26, 0x80
	s_addc_u32 s35, s27, 0
	s_mov_b64 s[38:39], s[26:27]
	s_mov_b64 s[36:37], s[24:25]
	ds_read_b128 v[16:19], v141
	ds_read_b128 v[20:23], v141 offset:1024
	ds_read_b128 v[32:35], v141 offset:2048
	ds_read_b128 v[36:39], v141 offset:3072
	s_mov_b64 s[58:59], s[56:57]
	s_add_u32 s56, s56, 0x80000
	s_mov_b32 m0, s51
	ds_read_b128 v[48:51], v140
	ds_read_b128 v[52:55], v140 offset:1024
	ds_read_b128 v[64:67], v140 offset:2048
	ds_read_b128 v[68:71], v140 offset:3072
	ds_read_b128 v[80:83], v140 offset:4096
	ds_read_b128 v[84:87], v140 offset:5120
	ds_read_b128 v[96:99], v140 offset:6144
	ds_read_b128 v[100:103], v140 offset:7168
	s_addc_u32 s57, s57, 0
	v_lshl_add_u64 v[112:113], s[58:59], 0, v[128:129]
	global_load_lds_dwordx4 v[112:113], off
	s_mov_b32 m0, s23
	v_lshl_add_u64 v[112:113], s[56:57], 0, v[128:129]
	global_load_lds_dwordx4 v[112:113], off
	s_waitcnt vmcnt(8)
	s_waitcnt lgkmcnt(0)
	s_barrier
	s_setprio 0
	s_waitcnt lgkmcnt(0)
	v_mfma_f32_16x16x128_f8f6f4 v[112:115], v[16:23], v[48:55], 0
	v_mfma_f32_16x16x128_f8f6f4 v[116:119], v[32:39], v[48:55], 0
	v_mfma_f32_16x16x128_f8f6f4 v[132:135], v[16:23], v[64:71], 0
	v_mfma_f32_16x16x128_f8f6f4 v[158:161], v[32:39], v[64:71], 0
	v_mfma_f32_16x16x128_f8f6f4 v[162:165], v[16:23], v[80:87], 0
	v_mfma_f32_16x16x128_f8f6f4 v[166:169], v[32:39], v[80:87], 0
	v_mfma_f32_16x16x128_f8f6f4 v[170:173], v[16:23], v[96:103], 0
	v_mfma_f32_16x16x128_f8f6f4 v[174:177], v[32:39], v[96:103], 0
	s_setprio 1
	s_barrier
	s_mov_b64 s[56:57], s[38:39]
	ds_read_b128 v[48:51], v140 offset:16384
	ds_read_b128 v[52:55], v140 offset:17408
	ds_read_b128 v[64:67], v140 offset:18432
	ds_read_b128 v[68:71], v140 offset:19456
	ds_read_b128 v[80:83], v140 offset:20480
	ds_read_b128 v[84:87], v140 offset:21504
	ds_read_b128 v[96:99], v140 offset:22528
	ds_read_b128 v[100:103], v140 offset:23552
	s_mov_b32 m0, s52
	v_lshl_add_u64 v[120:121], s[56:57], 0, v[130:131]
	s_add_u32 s56, s38, 0x8000
	s_addc_u32 s57, s39, 0
	global_load_lds_dwordx4 v[120:121], off
	s_mov_b32 m0, s47
	v_lshl_add_u64 v[120:121], s[56:57], 0, v[130:131]
	s_add_u32 s56, s38, 0x10000
	s_addc_u32 s57, s39, 0
	s_add_u32 s38, s38, 0x18000
	global_load_lds_dwordx4 v[120:121], off
	s_mov_b32 m0, s48
	v_lshl_add_u64 v[120:121], s[56:57], 0, v[130:131]
	s_addc_u32 s39, s39, 0
	global_load_lds_dwordx4 v[120:121], off
	s_mov_b32 m0, s40
	v_lshl_add_u64 v[120:121], s[38:39], 0, v[130:131]
	s_mov_b64 s[38:39], s[36:37]
	global_load_lds_dwordx4 v[120:121], off
	s_mov_b32 m0, s1
	v_lshl_add_u64 v[120:121], s[38:39], 0, v[128:129]
	s_add_u32 s38, s36, 0x80000
	s_addc_u32 s39, s37, 0
	global_load_lds_dwordx4 v[120:121], off
	s_mov_b32 m0, s2
	v_lshl_add_u64 v[120:121], s[38:39], 0, v[128:129]
	global_load_lds_dwordx4 v[120:121], off
	s_waitcnt vmcnt(8)
	s_waitcnt lgkmcnt(0)
	s_barrier
; #define G8_STAGE(bufoff, gbase, NM) do { _Pragma("unroll") for (int _i = 0; _i < 2; ++_i) { \
;     const char* _b = (const char*)(gbase) + (_i ? p2##NM : (size_t)0); asm volatile("" : "+s"(_b));     \
;     __builtin_amdgcn_global_load_lds((const unsigned*)(_b + voff##NM), (LAS unsigned*)(lds + (bufoff) + ldsw + _i * 8192), 16, 0, 0); } } while (0)
; #define G8_WAIT_V(n) asm volatile("s_waitcnt vmcnt(" #n ")" ::: "memory")
; #define G8_WAIT_L(n) asm volatile("s_waitcnt lgkmcnt(" #n ")" ::: "memory")
; #define G8_BAR __builtin_amdgcn_s_barrier()
; #define G8_SCHED __builtin_amdgcn_sched_barrier(0)
;     ...
;       G8_WAIT_V(8); G8_WAIT_L(0); G8_BAR; if (d0a) G8_MMA(1, 0, At, B0); if (d1a) G8_MMA(1, 1, At, B1); G8_BAR; G8_SCHED;
;       G8_LDB(B0, 1, 0); G8_LDB(B1, 1, 1); G8_SCHED; G8_LDA(At, 1, 0); G8_STAGE(G8_SA(0, 1), a2 + hstepA, A);
;       G8_WAIT_V(8); G8_WAIT_L(0); G8_BAR; if (d0b) G8_MMA(0, 0, At, B0); if (d1b) G8_MMA(0, 1, At, B1); G8_BAR; G8_SCHED;
;       G8_LDA(At, 1, 1); G8_STAGE(G8_SB(1, 0), b3, B); G8_STAGE(G8_SB(1, 1), b3 + hstepB, B); G8_STAGE(G8_SA(1, 0), a3, A);
;       G8_WAIT_V(8); G8_WAIT_L(0); G8_BAR; if (d0b) G8_MMA(1, 0, At, B0); if (d1b) G8_MMA(1, 1, At, B1); G8_BAR; G8_SCHED;
;     }
;     if (wr == 0) G8_BAR;
	s_setprio 0
	s_waitcnt lgkmcnt(0)
	v_mfma_f32_16x16x128_f8f6f4 v[178:181], v[16:23], v[48:55], 0
	v_mfma_f32_16x16x128_f8f6f4 v[182:185], v[32:39], v[48:55], 0
	v_mfma_f32_16x16x128_f8f6f4 v[186:189], v[16:23], v[64:71], 0
	v_mfma_f32_16x16x128_f8f6f4 v[190:193], v[32:39], v[64:71], 0
	v_mfma_f32_16x16x128_f8f6f4 v[194:197], v[16:23], v[80:87], 0
	v_mfma_f32_16x16x128_f8f6f4 v[202:205], v[32:39], v[80:87], 0
	v_mfma_f32_16x16x128_f8f6f4 v[206:209], v[16:23], v[96:103], 0
	v_mfma_f32_16x16x128_f8f6f4 v[210:213], v[32:39], v[96:103], 0
	s_setprio 1
	s_barrier
	v_add_u32_e32 v32, s54, v138
	ds_read_b128 v[16:19], v32
	ds_read_b128 v[20:23], v32 offset:1024
	ds_read_b128 v[142:145], v32 offset:2048
	ds_read_b128 v[146:149], v32 offset:3072
	s_add_u32 s38, s36, 0x100000
	s_addc_u32 s39, s37, 0
	s_add_u32 s36, s36, 0x180000
	s_mov_b32 m0, s3
	ds_read_b128 v[32:35], v140 offset:32768
	ds_read_b128 v[36:39], v140 offset:33792
	ds_read_b128 v[48:51], v140 offset:34816
	ds_read_b128 v[52:55], v140 offset:35840
	ds_read_b128 v[64:67], v140 offset:36864
	ds_read_b128 v[68:71], v140 offset:37888
	ds_read_b128 v[150:153], v140 offset:38912
	ds_read_b128 v[154:157], v140 offset:39936
	s_addc_u32 s37, s37, 0
	v_lshl_add_u64 v[80:81], s[38:39], 0, v[128:129]
	global_load_lds_dwordx4 v[80:81], off
	s_mov_b32 m0, s13
	v_lshl_add_u64 v[80:81], s[36:37], 0, v[128:129]
	global_load_lds_dwordx4 v[80:81], off
	s_waitcnt vmcnt(8)
	s_waitcnt lgkmcnt(0)
	s_barrier
	s_setprio 0
	s_waitcnt lgkmcnt(0)
	v_mfma_f32_16x16x128_f8f6f4 v[124:127], v[16:23], v[32:39], v[112:115]
	v_mfma_f32_16x16x128_f8f6f4 v[120:123], v[142:149], v[32:39], v[116:119]
	v_mfma_f32_16x16x128_f8f6f4 v[116:119], v[16:23], v[48:55], v[132:135]
	v_mfma_f32_16x16x128_f8f6f4 v[112:115], v[142:149], v[48:55], v[158:161]
	v_mfma_f32_16x16x128_f8f6f4 v[100:103], v[16:23], v[64:71], v[162:165]
	v_mfma_f32_16x16x128_f8f6f4 v[96:99], v[142:149], v[64:71], v[166:169]
	v_mfma_f32_16x16x128_f8f6f4 v[84:87], v[16:23], v[150:157], v[170:173]
	v_mfma_f32_16x16x128_f8f6f4 v[80:83], v[142:149], v[150:157], v[174:177]
	s_setprio 1
	s_barrier
	s_mov_b64 s[36:37], s[34:35]
	ds_read_b128 v[32:35], v140 offset:49152
	ds_read_b128 v[36:39], v140 offset:50176
	ds_read_b128 v[150:153], v140 offset:51200
	ds_read_b128 v[154:157], v140 offset:52224
	ds_read_b128 v[158:161], v140 offset:53248
	ds_read_b128 v[162:165], v140 offset:54272
	ds_read_b128 v[166:169], v140 offset:55296
	ds_read_b128 v[170:173], v140 offset:56320
	s_mov_b32 m0, s53
	v_lshl_add_u64 v[48:49], s[36:37], 0, v[130:131]
	s_add_u32 s36, s34, 0x8000
	s_addc_u32 s37, s35, 0
	global_load_lds_dwordx4 v[48:49], off
	s_mov_b32 m0, s41
	v_lshl_add_u64 v[48:49], s[36:37], 0, v[130:131]
	s_add_u32 s36, s34, 0x10000
	s_addc_u32 s37, s35, 0
	s_add_u32 s34, s34, 0x18000
	global_load_lds_dwordx4 v[48:49], off
	s_mov_b32 m0, s49
	v_lshl_add_u64 v[48:49], s[36:37], 0, v[130:131]
	s_addc_u32 s35, s35, 0
	global_load_lds_dwordx4 v[48:49], off
	s_mov_b32 m0, s50
	v_lshl_add_u64 v[48:49], s[34:35], 0, v[130:131]
	s_mov_b64 s[34:35], s[30:31]
	s_add_u32 s30, s30, 0x80000
	global_load_lds_dwordx4 v[48:49], off
	s_mov_b32 m0, s29
	v_lshl_add_u64 v[48:49], s[34:35], 0, v[128:129]
	s_addc_u32 s31, s31, 0
	global_load_lds_dwordx4 v[48:49], off
	s_mov_b32 m0, s33
	v_lshl_add_u64 v[48:49], s[30:31], 0, v[128:129]
	global_load_lds_dwordx4 v[48:49], off
	s_waitcnt vmcnt(8)
	s_waitcnt lgkmcnt(0)
	s_barrier
	s_setprio 0
	s_waitcnt lgkmcnt(0)
	v_mfma_f32_16x16x128_f8f6f4 v[68:71], v[16:23], v[32:39], v[178:181]
	v_mfma_f32_16x16x128_f8f6f4 v[64:67], v[142:149], v[32:39], v[182:185]
	v_mfma_f32_16x16x128_f8f6f4 v[52:55], v[16:23], v[150:157], v[186:189]
	v_mfma_f32_16x16x128_f8f6f4 v[48:51], v[142:149], v[150:157], v[190:193]
	v_mfma_f32_16x16x128_f8f6f4 v[36:39], v[16:23], v[158:165], v[194:197]
	v_mfma_f32_16x16x128_f8f6f4 v[32:35], v[142:149], v[158:165], v[202:205]
	v_mfma_f32_16x16x128_f8f6f4 v[20:23], v[16:23], v[166:173], v[206:209]
	v_mfma_f32_16x16x128_f8f6f4 v[16:19], v[142:149], v[166:173], v[210:213]
	s_setprio 1
	s_barrier
	s_andn2_b64 vcc, exec, s[10:11]
	s_cbranch_vccnz .LBB0_1047
	s_barrier
